# move W_ffn2_out weight conversion from P5 into the idle tail slot of the FFN2-in GEMM phase (P11)
# speedup vs baseline: 1.0058x; 1.0033x over previous
; #define LAS __attribute__((address_space(3)))
; template <int MODE, bool GAIN>
; __device__ __forceinline__ void transpose_loop2(const float* W, int K, int N, bf16_t* WT, const float* gain, LAS float* scr, int first, int n, int stride, int lane) {
;     for (int it = first; it < n; it += 2 * stride) { const int itB = it + stride; float ra[32], rb[32];
;         item_loads<MODE, GAIN>(W, N, gain, it, lane, ra); if (itB < n) item_loads<MODE, GAIN>(W, N, gain, itB, lane, rb);
;         transpose_finish<MODE>(ra, K, N, WT, scr, it, lane); if (itB < n) transpose_finish<MODE>(rb, K, N, WT, scr, itB, lane); }
; __global__ void __launch_bounds__(512, 2) mk_fwd(Args args) {
;     ...
;         transpose_loop2<0, false>(args.in[16], FF, DM, W1B, nullptr, scr, gw, I_1B, NGW, lane);
.LBB0_458:
	s_branch .LBB0_465

; #define LAS __attribute__((address_space(3)))
; __global__ void __launch_bounds__(512, 2) mk_fwd(Args args) {
;     ...
;         {
;             constexpr int NU = (M / 256) * (2 * FF / 256);
;             const int rounds = (NU + G - 1) / G, n_full = NU - (rounds - 1) * G;
;             const int nh = (n_full < G) ? G - n_full : G, hidx = (n_full < G) ? bx - n_full : bx;
;             if (hidx >= 0) {
;                 LAS float* scr = (LAS float*)(ldsl + wave * 16384);
;                 constexpr int I_1B = (FF / 64) * (DM / 32), I_IN = (DM / 64) * (NIN / 32), I_A = (1024 / 64) * (DM / 32), I_O = (DM / 64) * (DM / 32);
;                 constexpr int NLATE = I_1B + I_IN + 2 * I_A + I_O;
;                 const int first = hidx * 8 + wave, stride = nh * 8;
;                 transpose_loop2<0, false>(args.in[4], FF, DM, W1B, nullptr, scr, first, I_1B, stride, lane);
.LBB0_870:
	v_readfirstlane_b32 s26, v177
	s_lshr_b32 s26, s26, 6
	v_readlane_b32 s14, v239, 37
	s_abs_i32 s0, s14
	v_cvt_f32_u32_e32 v0, s0
	s_sub_i32 s3, 0, s0
	s_add_i32 s1, s14, 0x101f
	s_xor_b32 s2, s1, s14
	v_rcp_iflag_f32_e32 v0, v0
	s_abs_i32 s1, s1
	s_ashr_i32 s2, s2, 31
	v_mul_f32_e32 v0, 0x4f7ffffe, v0
	v_cvt_u32_f32_e32 v0, v0
	s_nop 0
	v_readfirstlane_b32 s12, v0
	s_mul_i32 s3, s3, s12
	s_mul_hi_u32 s3, s12, s3
	s_add_i32 s12, s12, s3
	s_mul_hi_u32 s3, s1, s12
	s_mul_i32 s12, s3, s0
	s_sub_i32 s1, s1, s12
	s_add_i32 s13, s3, 1
	s_sub_i32 s12, s1, s0
	s_cmp_ge_u32 s1, s0
	s_cselect_b32 s3, s13, s3
	s_cselect_b32 s1, s12, s1
	s_add_i32 s12, s3, 1
	s_cmp_ge_u32 s1, s0
	s_cselect_b32 s0, s12, s3
	s_xor_b32 s0, s0, s2
	s_not_b32 s1, s2
	s_add_i32 s0, s1, s0
	s_mul_i32 s0, s0, s14
	s_sub_i32 s0, 0x1020, s0
	s_cmp_lt_i32 s0, s14
	s_cselect_b32 s1, s0, 0
	s_sub_i32 s0, s61, s1
	s_cmp_lt_i32 s0, 0
	s_cbranch_scc1 .Ltail11_done
	v_readlane_b32 s2, v239, 37
	s_sub_i32 s16, s2, s1
	s_lshl_b32 s1, s26, 14
	s_lshl_b32 s0, s0, 3
	s_add_i32 s17, s1, 0
	s_add_i32 s14, s0, s26
	s_lshl_b32 s15, s16, 3
	s_cmpk_gt_i32 s14, 0x157f
	s_cbranch_scc1 .Ltail11_done
	v_and_b32_e32 v0, 31, v177
	v_lshlrev_b32_e32 v2, 2, v0
	v_mov_b32_e32 v3, 0
	v_readlane_b32 s44, v239, 27
	v_readlane_b32 s45, v239, 28
	v_add_u32_e32 v11, s17, v2
	v_readlane_b32 s0, v239, 38
	v_lshl_add_u64 v[0:1], s[44:45], 0, v[2:3]
	v_lshlrev_b32_e32 v2, 3, v177
	v_and_b32_e32 v2, 56, v2
	v_mul_u32_u24_e32 v6, 0x84, v2
	v_lshlrev_b32_e32 v2, 1, v2
	v_readlane_b32 s1, v239, 39
	v_lshrrev_b32_e32 v4, 5, v176
	v_lshrrev_b32_e32 v5, 3, v176
	v_lshl_add_u64 v[2:3], s[0:1], 0, v[2:3]
	s_mul_i32 s0, s14, 0x2b000
	v_mul_u32_u24_e32 v12, 0x84, v4
	v_lshlrev_b32_e32 v7, 2, v5
	s_movk_i32 s13, 0x1580
	v_mov_b32_e32 v10, s0
	v_add3_u32 v6, s17, v6, v7
	v_or_b32_e32 v7, 8, v5
	v_or_b32_e32 v8, 16, v5
	v_or_b32_e32 v9, 24, v5
	s_lshl_b32 s12, s16, 4
	v_mad_u32_u24 v10, v5, s13, v10
	s_mul_i32 s18, s16, 0x2b0000
	s_lshl_b32 s19, s14, 5
	s_lshl_b32 s20, s16, 9
	v_add_u32_e32 v11, v11, v12
	s_mov_b32 s21, s14
	s_branch .Ltail11_loop

; #define LAS __attribute__((address_space(3)))
; __device__ __forceinline__ unsigned cvt_pk_bf16(float lo, float hi) { unsigned r; asm volatile("v_cvt_pk_bf16_f32 %0, %1, %2" : "=v"(r) : "v"(lo), "v"(hi)); return r; }
; __device__ __forceinline__ int item_d0(int n0, int mode) { if (mode != 1) return n0; const int up = n0 >= FF, jj = up ? n0 - FF : n0; return (jj >> 7) * 256 + up * 128 + (jj & 127); }
; template <int MODE>
; __device__ __forceinline__ void transpose_finish(const float (&r)[32], int K, int N, bf16_t* WT, LAS float* scr, int item, int lane) {
;     const int nblk = N / 32, kb = item / nblk, nb = item % nblk, k0 = 64 * kb, d0 = item_d0(32 * nb, MODE);
; #pragma unroll
;     for (int i = 0; i < 32; ++i) { const int kk = 2 * i + (lane >> 5); scr[kk * 33 + (lane & 31)] = r[i]; }
;     asm volatile("s_waitcnt lgkmcnt(0)" ::: "memory");
;     const int c = lane & 7;
; #pragma unroll
;     for (int j = 0; j < 4; ++j) { const int n = (lane >> 3) + 8 * j; const LAS float* sp = scr + (8 * c) * 33 + n;
;         u32x4 o; o.x = cvt_pk_bf16(sp[0 * 33], sp[1 * 33]); o.y = cvt_pk_bf16(sp[2 * 33], sp[3 * 33]); o.z = cvt_pk_bf16(sp[4 * 33], sp[5 * 33]); o.w = cvt_pk_bf16(sp[6 * 33], sp[7 * 33]);
;         *(u32x4*)(WT + (size_t)(d0 + n) * K + k0 + 8 * c) = o; }
;     asm volatile("s_waitcnt lgkmcnt(0)" ::: "memory");
; }
; template <int MODE, bool GAIN>
; __device__ __forceinline__ void transpose_loop2(const float* W, int K, int N, bf16_t* WT, const float* gain, LAS float* scr, int first, int n, int stride, int lane) {
;     for (int it = first; it < n; it += 2 * stride) { const int itB = it + stride; float ra[32], rb[32];
;         item_loads<MODE, GAIN>(W, N, gain, it, lane, ra); if (itB < n) item_loads<MODE, GAIN>(W, N, gain, itB, lane, rb);
;         transpose_finish<MODE>(ra, K, N, WT, scr, it, lane); if (itB < n) transpose_finish<MODE>(rb, K, N, WT, scr, itB, lane); }
.Ltail11_b:
	s_waitcnt vmcnt(0)
	ds_write2_b32 v11, v44, v45 offset1:66
	ds_write2_b32 v11, v46, v48 offset0:132 offset1:198
	v_add_u32_e32 v44, 0x400, v11
	ds_write2_b32 v44, v47, v49 offset0:8 offset1:74
	ds_write2_b32 v44, v50, v51 offset0:140 offset1:206
	v_add_u32_e32 v45, 0x800, v11
	v_add_u32_e32 v46, 0xc00, v11
	v_add_u32_e32 v47, 0x1000, v11
	v_add_u32_e32 v48, 0x1400, v11
	v_add_u32_e32 v49, 0x1800, v11
	v_add_u32_e32 v50, 0x1c00, v11
	ds_write2_b32 v45, v52, v53 offset0:16 offset1:82
	ds_write2_b32 v45, v54, v56 offset0:148 offset1:214
	ds_write2_b32 v46, v55, v57 offset0:24 offset1:90
	ds_write2_b32 v46, v58, v59 offset0:156 offset1:222
	ds_write2_b32 v47, v60, v61 offset0:32 offset1:98
	ds_write2_b32 v47, v62, v64 offset0:164 offset1:230
	ds_write2_b32 v48, v63, v65 offset0:40 offset1:106
	ds_write2_b32 v48, v66, v67 offset0:172 offset1:238
	ds_write2_b32 v49, v68, v69 offset0:48 offset1:114
	ds_write2_b32 v49, v70, v72 offset0:180 offset1:246
	ds_write2_b32 v50, v71, v73 offset0:56 offset1:122
	ds_write2_b32 v50, v74, v75 offset0:188 offset1:254
	s_waitcnt lgkmcnt(0)
	ds_read2_b32 v[52:53], v6 offset1:33
	s_mul_i32 s22, s22, 0xff540000
	s_waitcnt lgkmcnt(0)
	v_cvt_pk_bf16_f32 v52, v52, v53
	ds_read2_b32 v[54:55], v6 offset0:66 offset1:99
	s_ashr_i32 s1, s0, 31
	v_add_u32_e32 v60, s22, v10
	s_waitcnt lgkmcnt(0)
	v_cvt_pk_bf16_f32 v53, v54, v55
	ds_read2_b32 v[54:55], v6 offset0:132 offset1:165
	v_lshl_add_u64 v[58:59], s[0:1], 1, v[2:3]
	v_ashrrev_i32_e32 v61, 31, v60
	s_waitcnt lgkmcnt(0)
	v_cvt_pk_bf16_f32 v54, v54, v55
	ds_read2_b32 v[56:57], v6 offset0:198 offset1:231
	s_waitcnt lgkmcnt(0)
	v_cvt_pk_bf16_f32 v55, v56, v57
	v_lshl_add_u64 v[62:63], v[60:61], 1, v[58:59]
	ds_read2_b32 v[56:57], v6 offset0:8 offset1:41
	global_store_dwordx4 v[62:63], v[52:55], off
	v_add_u32_e32 v62, 0xac00, v60
	v_ashrrev_i32_e32 v63, 31, v62
	s_waitcnt lgkmcnt(0)
	v_cvt_pk_bf16_f32 v52, v56, v57
	ds_read2_b32 v[54:55], v6 offset0:74 offset1:107
	s_waitcnt lgkmcnt(0)
	v_cvt_pk_bf16_f32 v53, v54, v55
	ds_read2_b32 v[54:55], v6 offset0:140 offset1:173
	s_waitcnt lgkmcnt(0)
	v_cvt_pk_bf16_f32 v54, v54, v55
	ds_read2_b32 v[56:57], v6 offset0:206 offset1:239
	s_waitcnt lgkmcnt(0)
	v_cvt_pk_bf16_f32 v55, v56, v57
	v_lshl_add_u64 v[62:63], v[62:63], 1, v[58:59]
	ds_read2_b32 v[56:57], v6 offset0:16 offset1:49
	global_store_dwordx4 v[62:63], v[52:55], off
	v_add_u32_e32 v62, 0x15800, v60
	v_ashrrev_i32_e32 v63, 31, v62
	s_waitcnt lgkmcnt(0)
	v_cvt_pk_bf16_f32 v52, v56, v57
	ds_read2_b32 v[54:55], v6 offset0:82 offset1:115
	s_waitcnt lgkmcnt(0)
	v_cvt_pk_bf16_f32 v53, v54, v55
	ds_read2_b32 v[54:55], v6 offset0:148 offset1:181
	s_waitcnt lgkmcnt(0)
	v_cvt_pk_bf16_f32 v54, v54, v55
	ds_read2_b32 v[56:57], v6 offset0:214 offset1:247
	s_waitcnt lgkmcnt(0)
	v_cvt_pk_bf16_f32 v55, v56, v57
	v_lshl_add_u64 v[62:63], v[62:63], 1, v[58:59]
	v_add_u32_e32 v60, 0x20400, v60
	ds_read2_b32 v[56:57], v6 offset0:24 offset1:57
	global_store_dwordx4 v[62:63], v[52:55], off
	v_ashrrev_i32_e32 v61, 31, v60
	v_lshl_add_u64 v[58:59], v[60:61], 1, v[58:59]
	s_waitcnt lgkmcnt(0)
	v_cvt_pk_bf16_f32 v52, v56, v57
	ds_read2_b32 v[54:55], v6 offset0:90 offset1:123
	s_waitcnt lgkmcnt(0)
	v_cvt_pk_bf16_f32 v53, v54, v55
	ds_read2_b32 v[54:55], v6 offset0:156 offset1:189
	s_waitcnt lgkmcnt(0)
	v_cvt_pk_bf16_f32 v54, v54, v55
	ds_read2_b32 v[56:57], v6 offset0:222 offset1:255
	s_waitcnt lgkmcnt(0)
	v_cvt_pk_bf16_f32 v55, v56, v57
	global_store_dwordx4 v[58:59], v[52:55], off
	s_waitcnt lgkmcnt(0)
	s_andn2_b64 vcc, exec, s[2:3]
	s_cbranch_vccnz .Ltail11_next
; #define LAS __attribute__((address_space(3)))
; __device__ __forceinline__ unsigned cvt_pk_bf16(float lo, float hi) { unsigned r; asm volatile("v_cvt_pk_bf16_f32 %0, %1, %2" : "=v"(r) : "v"(lo), "v"(hi)); return r; }
; __device__ __forceinline__ int item_d0(int n0, int mode) { if (mode != 1) return n0; const int up = n0 >= FF, jj = up ? n0 - FF : n0; return (jj >> 7) * 256 + up * 128 + (jj & 127); }
; __device__ __forceinline__ void xcd_barrier(const XcdBarrier& b) {
;     asm volatile("s_waitcnt vmcnt(0)" ::: "memory");
;     __syncthreads();
;     if (threadIdx.x == 0) {
;         unsigned* bar = b.bar;
;         __builtin_amdgcn_s_waitcnt(0);
;         unsigned nloc = b.st[0], nx = b.st[1];
;         if (nloc == 0u) { xcd_barrier_complete(bar, b.x, nloc, nx); b.st[0] = nloc; b.st[1] = nx; }
; template <int MODE>
; __device__ __forceinline__ void transpose_finish(const float (&r)[32], int K, int N, bf16_t* WT, LAS float* scr, int item, int lane) {
;     const int nblk = N / 32, kb = item / nblk, nb = item % nblk, k0 = 64 * kb, d0 = item_d0(32 * nb, MODE);
; #pragma unroll
;     for (int i = 0; i < 32; ++i) { const int kk = 2 * i + (lane >> 5); scr[kk * 33 + (lane & 31)] = r[i]; }
;     asm volatile("s_waitcnt lgkmcnt(0)" ::: "memory");
;     const int c = lane & 7;
; #pragma unroll
;     for (int j = 0; j < 4; ++j) { const int n = (lane >> 3) + 8 * j; const LAS float* sp = scr + (8 * c) * 33 + n;
;         u32x4 o; o.x = cvt_pk_bf16(sp[0 * 33], sp[1 * 33]); o.y = cvt_pk_bf16(sp[2 * 33], sp[3 * 33]); o.z = cvt_pk_bf16(sp[4 * 33], sp[5 * 33]); o.w = cvt_pk_bf16(sp[6 * 33], sp[7 * 33]);
;         *(u32x4*)(WT + (size_t)(d0 + n) * K + k0 + 8 * c) = o; }
;     asm volatile("s_waitcnt lgkmcnt(0)" ::: "memory");
; }
	s_ashr_i32 s0, s23, 31
	s_lshr_b32 s0, s0, 26
	s_add_i32 s0, s23, s0
	s_andn2_b32 s0, s0, 63
	s_sub_i32 s1, s23, s0
	ds_write2_b32 v11, v12, v13 offset1:66
	ds_write2_b32 v11, v14, v15 offset0:132 offset1:198
	ds_write2_b32 v44, v16, v17 offset0:8 offset1:74
	ds_write2_b32 v44, v18, v19 offset0:140 offset1:206
	ds_write2_b32 v45, v20, v21 offset0:16 offset1:82
	ds_write2_b32 v45, v22, v23 offset0:148 offset1:214
	ds_write2_b32 v46, v24, v25 offset0:24 offset1:90
	ds_write2_b32 v46, v26, v27 offset0:156 offset1:222
	ds_write2_b32 v47, v28, v29 offset0:32 offset1:98
	ds_write2_b32 v47, v30, v31 offset0:164 offset1:230
	ds_write2_b32 v48, v32, v33 offset0:40 offset1:106
	ds_write2_b32 v48, v34, v35 offset0:172 offset1:238
	ds_write2_b32 v49, v36, v37 offset0:48 offset1:114
	ds_write2_b32 v49, v38, v39 offset0:180 offset1:246
	ds_write2_b32 v50, v40, v41 offset0:56 offset1:122
	ds_write2_b32 v50, v42, v43 offset0:188 offset1:254
	s_lshl_b32 s2, s1, 5
	s_waitcnt lgkmcnt(0)
	v_or_b32_e32 v52, s2, v5
	ds_read2_b32 v[44:45], v6 offset1:33
	s_ashr_i32 s1, s0, 31
	v_mul_lo_u32 v52, v52, s13
	s_waitcnt lgkmcnt(0)
	v_cvt_pk_bf16_f32 v44, v44, v45
	ds_read2_b32 v[46:47], v6 offset0:66 offset1:99
	v_lshl_add_u64 v[50:51], s[0:1], 1, v[2:3]
	v_ashrrev_i32_e32 v53, 31, v52
	s_waitcnt lgkmcnt(0)
	v_cvt_pk_bf16_f32 v45, v46, v47
	ds_read2_b32 v[46:47], v6 offset0:132 offset1:165
	v_lshl_add_u64 v[52:53], v[52:53], 1, v[50:51]
	s_waitcnt lgkmcnt(0)
	v_cvt_pk_bf16_f32 v46, v46, v47
	ds_read2_b32 v[48:49], v6 offset0:198 offset1:231
	s_waitcnt lgkmcnt(0)
	v_cvt_pk_bf16_f32 v47, v48, v49
	global_store_dwordx4 v[52:53], v[44:47], off
	v_or_b32_e32 v52, s2, v7
	v_mul_lo_u32 v52, v52, s13
	ds_read2_b32 v[48:49], v6 offset0:8 offset1:41
	s_waitcnt lgkmcnt(0)
	v_cvt_pk_bf16_f32 v44, v48, v49
	ds_read2_b32 v[46:47], v6 offset0:74 offset1:107
	v_ashrrev_i32_e32 v53, 31, v52
	s_waitcnt lgkmcnt(0)
	v_cvt_pk_bf16_f32 v45, v46, v47
	ds_read2_b32 v[46:47], v6 offset0:140 offset1:173
	v_lshl_add_u64 v[52:53], v[52:53], 1, v[50:51]
	s_waitcnt lgkmcnt(0)
	v_cvt_pk_bf16_f32 v46, v46, v47
	ds_read2_b32 v[48:49], v6 offset0:206 offset1:239
	s_waitcnt lgkmcnt(0)
	v_cvt_pk_bf16_f32 v47, v48, v49
	global_store_dwordx4 v[52:53], v[44:47], off
	v_or_b32_e32 v52, s2, v8
	ds_read2_b32 v[48:49], v6 offset0:16 offset1:49
	s_waitcnt lgkmcnt(0)
	v_cvt_pk_bf16_f32 v44, v48, v49
	ds_read2_b32 v[46:47], v6 offset0:82 offset1:115
	v_mul_lo_u32 v52, v52, s13
	s_waitcnt lgkmcnt(0)
	v_cvt_pk_bf16_f32 v45, v46, v47
	ds_read2_b32 v[46:47], v6 offset0:148 offset1:181
	v_ashrrev_i32_e32 v53, 31, v52
	s_waitcnt lgkmcnt(0)
	v_cvt_pk_bf16_f32 v46, v46, v47
	ds_read2_b32 v[48:49], v6 offset0:214 offset1:247
	s_waitcnt lgkmcnt(0)
	v_cvt_pk_bf16_f32 v47, v48, v49
	v_lshl_add_u64 v[52:53], v[52:53], 1, v[50:51]
	ds_read2_b32 v[48:49], v6 offset0:24 offset1:57
	global_store_dwordx4 v[52:53], v[44:47], off
	s_waitcnt lgkmcnt(0)
	s_nop 0
	v_cvt_pk_bf16_f32 v44, v48, v49
	ds_read2_b32 v[46:47], v6 offset0:90 offset1:123
	s_waitcnt lgkmcnt(0)
	v_cvt_pk_bf16_f32 v45, v46, v47
	ds_read2_b32 v[46:47], v6 offset0:156 offset1:189
	s_waitcnt lgkmcnt(0)
	v_cvt_pk_bf16_f32 v46, v46, v47
	v_or_b32_e32 v47, s2, v9
	v_mul_lo_u32 v52, v47, s13
	ds_read2_b32 v[48:49], v6 offset0:222 offset1:255
	v_ashrrev_i32_e32 v53, 31, v52
	s_waitcnt lgkmcnt(0)
	v_cvt_pk_bf16_f32 v47, v48, v49
	v_lshl_add_u64 v[48:49], v[52:53], 1, v[50:51]
	global_store_dwordx4 v[48:49], v[44:47], off
	s_waitcnt lgkmcnt(0)
	s_branch .Ltail11_next
.Ltail11_done:
	s_cmp_gt_i32 s73, 12
	s_cselect_b64 s[0:1], -1, 0
	s_and_b64 s[2:3], s[4:5], s[0:1]
	s_andn2_b64 vcc, exec, s[2:3]
	s_cbranch_vccnz .LBB0_924
	s_waitcnt vmcnt(0)
	s_waitcnt lgkmcnt(0)
	s_barrier
	s_mov_b64 s[2:3], exec
	v_readlane_b32 s4, v239, 21
	v_readlane_b32 s5, v239, 22
	s_and_b64 s[4:5], s[2:3], s[4:5]
	s_mov_b64 exec, s[4:5]
	s_cbranch_execz .LBB0_923
	s_add_i32 s4, 0, 0x22400
	v_mov_b32_e32 v0, s4
	s_waitcnt vmcnt(0) expcnt(0) lgkmcnt(0)
	ds_read_b32 v2, v0
	s_add_i32 s4, 0, 0x22404
	v_mov_b32_e32 v0, s4
	ds_read_b32 v0, v0
	s_waitcnt lgkmcnt(1)
	v_cmp_ne_u32_e32 vcc, 0, v2
	s_cbranch_vccnz .LBB0_887
	v_readlane_b32 s4, v239, 0
	v_readlane_b32 s5, v239, 1
	s_load_dwordx2 s[8:9], s[4:5], 0x4
	s_add_u32 s4, s70, 0x48200
	s_addc_u32 s5, s71, 0
	s_add_u32 s6, s70, 0x48400
	s_addc_u32 s7, s71, 0
	s_waitcnt lgkmcnt(0)
	s_mul_i32 s33, s8, s97
	s_add_u32 s8, s70, 0x48500
	s_mul_i32 s33, s33, s9
	s_addc_u32 s9, s71, 0
	s_add_u32 s10, s70, 0x48600
	s_addc_u32 s11, s71, 0
	s_add_u32 s12, s70, 0x48700
	s_addc_u32 s13, s71, 0
	s_add_u32 s14, s70, 0x48800
	s_addc_u32 s15, s71, 0
	s_add_u32 s16, s70, 0x48900
	s_addc_u32 s17, s71, 0
	s_add_u32 s18, s70, 0x48a00
	s_addc_u32 s19, s71, 0
	s_add_u32 s20, s70, 0x48b00
	s_addc_u32 s21, s71, 0
	s_add_u32 s22, s70, 0x48c00
	s_addc_u32 s23, s71, 0
	s_add_u32 s24, s70, 0x48d00
	s_addc_u32 s25, s71, 0
	s_add_u32 s26, s70, 0x48e00
	s_addc_u32 s27, s71, 0
	s_add_u32 s28, s70, 0x48f00
	s_addc_u32 s29, s71, 0
	s_add_u32 s30, s70, 0x49000
	s_addc_u32 s31, s71, 0
	s_add_u32 s34, s70, 0x49100
	s_addc_u32 s35, s71, 0
	s_add_u32 s36, s70, 0x49200
	s_addc_u32 s37, s71, 0
	s_add_u32 s38, s70, 0x49300
	s_addc_u32 s39, s71, 0
	s_mov_b32 s46, 1
	v_mov_b32_e32 v16, 0
	s_branch .LBB0_875
